# EpiResid epilogue: XF loads hoisted 3 row-blocks ahead into dead fragment VGPRs with counted vmcnt (de-serialized load-wait-store ladder); plus MFMA pair order and early barrier
# speedup vs baseline: 1.0132x; 1.0040x over previous
.LBB0_989:
	v_and_b32_e32 v148, 64, v153
	v_xor_b32_e32 v147, 16, v153
	v_add_u32_e32 v148, 64, v148
	v_cmp_lt_i32_e32 vcc, v147, v148
	v_lshl_add_u32 v146, s25, 8, v1
	v_readlane_b32 s2, v250, 9
	v_cndmask_b32_e32 v147, v153, v147, vcc
	v_lshlrev_b32_e32 v167, 2, v147
	v_xor_b32_e32 v147, 32, v153
	v_cmp_lt_i32_e32 vcc, v147, v148
	v_lshl_or_b32 v144, s23, 8, v151
	v_readlane_b32 s3, v250, 10
	v_cndmask_b32_e32 v147, v153, v147, vcc
	v_lshlrev_b32_e32 v166, 2, v147
	v_ashrrev_i32_e32 v147, 31, v146
	v_lshlrev_b64 v[148:149], 13, v[146:147]
	v_ashrrev_i32_e32 v145, 31, v144
	v_lshl_add_u64 v[148:149], s[2:3], 0, v[148:149]
	v_lshl_add_u64 v[148:149], v[144:145], 2, v[148:149]
	v_mov_b32_e32 v204, v148
	v_mov_b32_e32 v205, v149
	global_load_dwordx4 v[176:179], v[148:149], off offset:16
	global_load_dwordx4 v[180:183], v[148:149], off
	global_load_dwordx4 v[184:187], v[148:149], off offset:528
	global_load_dwordx4 v[188:191], v[148:149], off offset:512
	s_mov_b32 s88, 0x20000
	s_mov_b32 s89, 0
	v_lshl_add_u64 v[212:213], v[204:205], 0, s[88:89]
	global_load_dwordx4 v[228:231], v[212:213], off offset:16
	global_load_dwordx4 v[232:235], v[212:213], off
	global_load_dwordx4 v[236:239], v[212:213], off offset:528
	global_load_dwordx4 v[240:243], v[212:213], off offset:512
	s_mov_b32 s88, 0x40000
	s_mov_b32 s89, 0
	v_lshl_add_u64 v[214:215], v[204:205], 0, s[88:89]
	global_load_dwordx4 v[192:195], v[214:215], off offset:16
	global_load_dwordx4 v[196:199], v[214:215], off
	global_load_dwordx4 v[200:203], v[214:215], off offset:528
	global_load_dwordx4 v[244:247], v[214:215], off offset:512
	v_readlane_b32 s2, v252, 15
	v_readlane_b32 s3, v252, 16
	s_lshl_b32 s0, s23, 2
	s_ashr_i32 s1, s0, 31
	s_waitcnt vmcnt(10)
	v_pk_fma_f32 v[124:125], v[124:125], 0.5, v[176:177] op_sel_hi:[1,0,1]
	v_pk_fma_f32 v[130:131], v[130:131], 0.5, v[182:183] op_sel_hi:[1,0,1]
	v_pk_fma_f32 v[128:129], v[128:129], 0.5, v[180:181] op_sel_hi:[1,0,1]
	v_mul_f32_e32 v169, v131, v131
	v_mul_f32_e32 v168, v129, v129
	v_pk_fma_f32 v[126:127], v[126:127], 0.5, v[178:179] op_sel_hi:[1,0,1]
	v_fmac_f32_e32 v168, v128, v128
	v_fmac_f32_e32 v169, v130, v130
	v_add_f32_e32 v168, v168, v169
	v_mul_f32_e32 v169, v125, v125
	v_mul_f32_e32 v170, v127, v127
	global_store_dwordx4 v[148:149], v[128:131], off
	global_store_dwordx4 v[148:149], v[124:127], off offset:16
	v_fmac_f32_e32 v169, v124, v124
	v_fmac_f32_e32 v170, v126, v126
	v_cvt_pk_bf16_f32 v128, v128, v129
	v_cvt_pk_bf16_f32 v129, v130, v131
	v_cvt_pk_bf16_f32 v130, v124, v125
	v_lshlrev_b64 v[124:125], 12, v[146:147]
	v_add_f32_e32 v169, v169, v170
	v_lshl_add_u64 v[124:125], s[2:3], 0, v[124:125]
	v_add_f32_e32 v170, v168, v169
	v_cvt_pk_bf16_f32 v131, v126, v127
	v_lshl_add_u64 v[168:169], v[144:145], 1, v[124:125]
	global_store_dwordx4 v[168:169], v[128:131], off
	s_waitcnt vmcnt(11)
	v_pk_fma_f32 v[116:117], v[116:117], 0.5, v[184:185] op_sel_hi:[1,0,1]
	v_pk_fma_f32 v[122:123], v[122:123], 0.5, v[190:191] op_sel_hi:[1,0,1]
	v_pk_fma_f32 v[120:121], v[120:121], 0.5, v[188:189] op_sel_hi:[1,0,1]
	v_mul_f32_e32 v125, v123, v123
	v_mul_f32_e32 v124, v121, v121
	v_pk_fma_f32 v[118:119], v[118:119], 0.5, v[186:187] op_sel_hi:[1,0,1]
	s_mov_b32 s88, 0x60000
	s_mov_b32 s89, 0
	v_lshl_add_u64 v[212:213], v[204:205], 0, s[88:89]
	global_load_dwordx4 v[176:179], v[212:213], off offset:16
	global_load_dwordx4 v[180:183], v[212:213], off
	global_load_dwordx4 v[184:187], v[212:213], off offset:528
	global_load_dwordx4 v[188:191], v[212:213], off offset:512
	v_fmac_f32_e32 v124, v120, v120
	v_fmac_f32_e32 v125, v122, v122
	v_add_f32_e32 v124, v124, v125
	v_mul_f32_e32 v125, v117, v117
	v_mul_f32_e32 v126, v119, v119
	v_fmac_f32_e32 v125, v116, v116
	v_fmac_f32_e32 v126, v118, v118
	v_add_f32_e32 v125, v125, v126
	v_add_f32_e32 v124, v124, v125
	v_add_f32_e32 v124, v170, v124
	global_store_dwordx4 v[148:149], v[120:123], off offset:512
	global_store_dwordx4 v[148:149], v[116:119], off offset:528
	s_nop 0
	v_cvt_pk_bf16_f32 v120, v120, v121
	v_cvt_pk_bf16_f32 v121, v122, v123
	v_cvt_pk_bf16_f32 v122, v116, v117
	ds_bpermute_b32 v116, v167, v124
	v_cvt_pk_bf16_f32 v123, v118, v119
	global_store_dwordx4 v[168:169], v[120:123], off offset:256
	s_waitcnt lgkmcnt(0)
	v_add_f32_e32 v116, v124, v116
	ds_bpermute_b32 v117, v166, v116
	s_and_saveexec_b64 s[4:5], s[36:37]
	s_cbranch_execz .LBB0_991
	v_readlane_b32 s2, v250, 11
	v_lshlrev_b64 v[118:119], 7, v[146:147]
	v_readlane_b32 s3, v250, 12
	s_lshl_b32 s6, s30, 2
	s_waitcnt lgkmcnt(0)
	v_add_f32_e32 v116, v116, v117
	v_lshl_add_u64 v[118:119], s[2:3], 0, v[118:119]
	v_readlane_b32 s2, v253, 17
	v_readlane_b32 s3, v253, 18
	v_lshl_add_u64 v[118:119], s[0:1], 2, v[118:119]
	s_mov_b32 s7, s3
	v_writelane_b32 v253, s2, 17
	v_lshl_add_u64 v[118:119], v[118:119], 0, s[6:7]
	global_store_dword v[118:119], v116, off
	v_writelane_b32 v253, s3, 18
.LBB0_991:
	s_or_b64 exec, exec, s[4:5]
	v_or_b32_e32 v116, 16, v146
	s_waitcnt lgkmcnt(0)
	v_ashrrev_i32_e32 v117, 31, v116
	v_readlane_b32 s2, v250, 9
	v_lshlrev_b64 v[118:119], 13, v[116:117]
	v_readlane_b32 s3, v250, 10
	s_nop 1
	v_lshl_add_u64 v[118:119], s[2:3], 0, v[118:119]
	v_lshl_add_u64 v[118:119], v[144:145], 2, v[118:119]
	v_readlane_b32 s2, v252, 15
	v_readlane_b32 s3, v252, 16
	s_waitcnt vmcnt(16)
	v_pk_fma_f32 v[108:109], v[108:109], 0.5, v[228:229] op_sel_hi:[1,0,1]
	v_pk_fma_f32 v[114:115], v[114:115], 0.5, v[234:235] op_sel_hi:[1,0,1]
	v_pk_fma_f32 v[112:113], v[112:113], 0.5, v[232:233] op_sel_hi:[1,0,1]
	v_mul_f32_e32 v121, v115, v115
	v_mul_f32_e32 v120, v113, v113
	v_pk_fma_f32 v[110:111], v[110:111], 0.5, v[230:231] op_sel_hi:[1,0,1]
	v_fmac_f32_e32 v120, v112, v112
	v_fmac_f32_e32 v121, v114, v114
	v_add_f32_e32 v120, v120, v121
	v_mul_f32_e32 v121, v109, v109
	v_mul_f32_e32 v122, v111, v111
	global_store_dwordx4 v[118:119], v[112:115], off
	global_store_dwordx4 v[118:119], v[108:111], off offset:16
	v_fmac_f32_e32 v121, v108, v108
	v_fmac_f32_e32 v122, v110, v110
	v_cvt_pk_bf16_f32 v112, v112, v113
	v_cvt_pk_bf16_f32 v113, v114, v115
	v_cvt_pk_bf16_f32 v114, v108, v109
	v_lshlrev_b64 v[108:109], 12, v[116:117]
	v_add_f32_e32 v121, v121, v122
	v_lshl_add_u64 v[108:109], s[2:3], 0, v[108:109]
	v_add_f32_e32 v122, v120, v121
	v_cvt_pk_bf16_f32 v115, v110, v111
	v_lshl_add_u64 v[120:121], v[144:145], 1, v[108:109]
	global_store_dwordx4 v[120:121], v[112:115], off
	s_waitcnt vmcnt(17)
	v_pk_fma_f32 v[100:101], v[100:101], 0.5, v[236:237] op_sel_hi:[1,0,1]
	v_pk_fma_f32 v[106:107], v[106:107], 0.5, v[242:243] op_sel_hi:[1,0,1]
	v_pk_fma_f32 v[104:105], v[104:105], 0.5, v[240:241] op_sel_hi:[1,0,1]
	v_mul_f32_e32 v109, v107, v107
	v_mul_f32_e32 v108, v105, v105
	v_pk_fma_f32 v[102:103], v[102:103], 0.5, v[238:239] op_sel_hi:[1,0,1]
	s_mov_b32 s88, 0x100000
	s_mov_b32 s89, 0
	v_lshl_add_u64 v[212:213], v[204:205], 0, s[88:89]
	global_load_dwordx4 v[228:231], v[212:213], off offset:16
	global_load_dwordx4 v[232:235], v[212:213], off
	global_load_dwordx4 v[236:239], v[212:213], off offset:528
	global_load_dwordx4 v[240:243], v[212:213], off offset:512
	v_fmac_f32_e32 v108, v104, v104
	v_fmac_f32_e32 v109, v106, v106
	v_add_f32_e32 v108, v108, v109
	v_mul_f32_e32 v109, v101, v101
	v_mul_f32_e32 v110, v103, v103
	v_fmac_f32_e32 v109, v100, v100
	v_fmac_f32_e32 v110, v102, v102
	v_add_f32_e32 v109, v109, v110
	v_add_f32_e32 v108, v108, v109
	v_add_f32_e32 v108, v122, v108
	global_store_dwordx4 v[118:119], v[104:107], off offset:512
	global_store_dwordx4 v[118:119], v[100:103], off offset:528
	s_nop 0
	v_cvt_pk_bf16_f32 v104, v104, v105
	v_cvt_pk_bf16_f32 v105, v106, v107
	v_cvt_pk_bf16_f32 v106, v100, v101
	ds_bpermute_b32 v100, v167, v108
	v_cvt_pk_bf16_f32 v107, v102, v103
	global_store_dwordx4 v[120:121], v[104:107], off offset:256
	s_waitcnt lgkmcnt(0)
	v_add_f32_e32 v100, v108, v100
	ds_bpermute_b32 v101, v166, v100
	s_and_saveexec_b64 s[4:5], s[36:37]
	s_cbranch_execz .LBB0_993
	v_readlane_b32 s2, v250, 11
	v_lshlrev_b64 v[102:103], 7, v[116:117]
	v_readlane_b32 s3, v250, 12
	s_lshl_b32 s6, s30, 2
	s_waitcnt lgkmcnt(0)
	v_add_f32_e32 v100, v100, v101
	v_lshl_add_u64 v[102:103], s[2:3], 0, v[102:103]
	v_readlane_b32 s2, v253, 17
	v_readlane_b32 s3, v253, 18
	v_lshl_add_u64 v[102:103], s[0:1], 2, v[102:103]
	s_mov_b32 s7, s3
	v_writelane_b32 v253, s2, 17
	v_lshl_add_u64 v[102:103], v[102:103], 0, s[6:7]
	global_store_dword v[102:103], v100, off
	v_writelane_b32 v253, s3, 18
.LBB0_993:
	s_or_b64 exec, exec, s[4:5]
	v_or_b32_e32 v100, 32, v146
	s_waitcnt lgkmcnt(0)
	v_ashrrev_i32_e32 v101, 31, v100
	v_readlane_b32 s2, v250, 9
	v_lshlrev_b64 v[102:103], 13, v[100:101]
	v_readlane_b32 s3, v250, 10
	s_nop 1
	v_lshl_add_u64 v[102:103], s[2:3], 0, v[102:103]
	v_lshl_add_u64 v[102:103], v[144:145], 2, v[102:103]
	v_readlane_b32 s2, v252, 15
	v_readlane_b32 s3, v252, 16
	s_waitcnt vmcnt(22)
	v_pk_fma_f32 v[92:93], v[92:93], 0.5, v[192:193] op_sel_hi:[1,0,1]
	v_pk_fma_f32 v[98:99], v[98:99], 0.5, v[198:199] op_sel_hi:[1,0,1]
	v_pk_fma_f32 v[96:97], v[96:97], 0.5, v[196:197] op_sel_hi:[1,0,1]
	v_mul_f32_e32 v105, v99, v99
	v_mul_f32_e32 v104, v97, v97
	v_pk_fma_f32 v[94:95], v[94:95], 0.5, v[194:195] op_sel_hi:[1,0,1]
	v_fmac_f32_e32 v104, v96, v96
	v_fmac_f32_e32 v105, v98, v98
	v_add_f32_e32 v104, v104, v105
	v_mul_f32_e32 v105, v93, v93
	v_mul_f32_e32 v106, v95, v95
	global_store_dwordx4 v[102:103], v[96:99], off
	global_store_dwordx4 v[102:103], v[92:95], off offset:16
	v_fmac_f32_e32 v105, v92, v92
	v_fmac_f32_e32 v106, v94, v94
	v_cvt_pk_bf16_f32 v96, v96, v97
	v_cvt_pk_bf16_f32 v97, v98, v99
	v_cvt_pk_bf16_f32 v98, v92, v93
	v_lshlrev_b64 v[92:93], 12, v[100:101]
	v_add_f32_e32 v105, v105, v106
	v_lshl_add_u64 v[92:93], s[2:3], 0, v[92:93]
	v_add_f32_e32 v106, v104, v105
	v_cvt_pk_bf16_f32 v99, v94, v95
	v_lshl_add_u64 v[104:105], v[144:145], 1, v[92:93]
	global_store_dwordx4 v[104:105], v[96:99], off
	s_waitcnt vmcnt(23)
	v_pk_fma_f32 v[84:85], v[84:85], 0.5, v[200:201] op_sel_hi:[1,0,1]
	v_pk_fma_f32 v[90:91], v[90:91], 0.5, v[246:247] op_sel_hi:[1,0,1]
	v_pk_fma_f32 v[88:89], v[88:89], 0.5, v[244:245] op_sel_hi:[1,0,1]
	v_mul_f32_e32 v93, v91, v91
	v_mul_f32_e32 v92, v89, v89
	v_pk_fma_f32 v[86:87], v[86:87], 0.5, v[202:203] op_sel_hi:[1,0,1]
	s_mov_b32 s88, 0x120000
	s_mov_b32 s89, 0
	v_lshl_add_u64 v[212:213], v[204:205], 0, s[88:89]
	global_load_dwordx4 v[192:195], v[212:213], off offset:16
	global_load_dwordx4 v[196:199], v[212:213], off
	global_load_dwordx4 v[200:203], v[212:213], off offset:528
	global_load_dwordx4 v[244:247], v[212:213], off offset:512
	v_fmac_f32_e32 v92, v88, v88
	v_fmac_f32_e32 v93, v90, v90
	v_add_f32_e32 v92, v92, v93
	v_mul_f32_e32 v93, v85, v85
	v_mul_f32_e32 v94, v87, v87
	v_fmac_f32_e32 v93, v84, v84
	v_fmac_f32_e32 v94, v86, v86
	v_add_f32_e32 v93, v93, v94
	v_add_f32_e32 v92, v92, v93
	v_add_f32_e32 v92, v106, v92
	global_store_dwordx4 v[102:103], v[88:91], off offset:512
	global_store_dwordx4 v[102:103], v[84:87], off offset:528
	s_nop 0
	v_cvt_pk_bf16_f32 v88, v88, v89
	v_cvt_pk_bf16_f32 v89, v90, v91
	v_cvt_pk_bf16_f32 v90, v84, v85
	ds_bpermute_b32 v84, v167, v92
	v_cvt_pk_bf16_f32 v91, v86, v87
	global_store_dwordx4 v[104:105], v[88:91], off offset:256
	s_waitcnt lgkmcnt(0)
	v_add_f32_e32 v84, v92, v84
	ds_bpermute_b32 v85, v166, v84
	s_and_saveexec_b64 s[4:5], s[36:37]
	s_cbranch_execz .LBB0_995
	v_readlane_b32 s2, v250, 11
	v_lshlrev_b64 v[86:87], 7, v[100:101]
	v_readlane_b32 s3, v250, 12
	s_lshl_b32 s6, s30, 2
	s_waitcnt lgkmcnt(0)
	v_add_f32_e32 v84, v84, v85
	v_lshl_add_u64 v[86:87], s[2:3], 0, v[86:87]
	v_readlane_b32 s2, v253, 17
	v_readlane_b32 s3, v253, 18
	v_lshl_add_u64 v[86:87], s[0:1], 2, v[86:87]
	s_mov_b32 s7, s3
	v_writelane_b32 v253, s2, 17
	v_lshl_add_u64 v[86:87], v[86:87], 0, s[6:7]
	global_store_dword v[86:87], v84, off
	v_writelane_b32 v253, s3, 18
.LBB0_995:
	s_or_b64 exec, exec, s[4:5]
	v_or_b32_e32 v84, 48, v146
	s_waitcnt lgkmcnt(0)
	v_ashrrev_i32_e32 v85, 31, v84
	v_readlane_b32 s2, v250, 9
	v_lshlrev_b64 v[86:87], 13, v[84:85]
	v_readlane_b32 s3, v250, 10
	s_nop 1
	v_lshl_add_u64 v[86:87], s[2:3], 0, v[86:87]
	v_lshl_add_u64 v[86:87], v[144:145], 2, v[86:87]
	v_readlane_b32 s2, v252, 15
	v_readlane_b32 s3, v252, 16
	s_waitcnt vmcnt(25)
	v_pk_fma_f32 v[76:77], v[76:77], 0.5, v[176:177] op_sel_hi:[1,0,1]
	v_pk_fma_f32 v[82:83], v[82:83], 0.5, v[182:183] op_sel_hi:[1,0,1]
	v_pk_fma_f32 v[80:81], v[80:81], 0.5, v[180:181] op_sel_hi:[1,0,1]
	v_mul_f32_e32 v89, v83, v83
	v_mul_f32_e32 v88, v81, v81
	v_pk_fma_f32 v[78:79], v[78:79], 0.5, v[178:179] op_sel_hi:[1,0,1]
	v_fmac_f32_e32 v88, v80, v80
	v_fmac_f32_e32 v89, v82, v82
	v_add_f32_e32 v88, v88, v89
	v_mul_f32_e32 v89, v77, v77
	v_mul_f32_e32 v90, v79, v79
	global_store_dwordx4 v[86:87], v[80:83], off
	global_store_dwordx4 v[86:87], v[76:79], off offset:16
	v_fmac_f32_e32 v89, v76, v76
	v_fmac_f32_e32 v90, v78, v78
	v_cvt_pk_bf16_f32 v80, v80, v81
	v_cvt_pk_bf16_f32 v81, v82, v83
	v_cvt_pk_bf16_f32 v82, v76, v77
	v_lshlrev_b64 v[76:77], 12, v[84:85]
	v_add_f32_e32 v89, v89, v90
	v_lshl_add_u64 v[76:77], s[2:3], 0, v[76:77]
	v_add_f32_e32 v90, v88, v89
	v_cvt_pk_bf16_f32 v83, v78, v79
	v_lshl_add_u64 v[88:89], v[144:145], 1, v[76:77]
	global_store_dwordx4 v[88:89], v[80:83], off
	s_waitcnt vmcnt(26)
	v_pk_fma_f32 v[68:69], v[68:69], 0.5, v[184:185] op_sel_hi:[1,0,1]
	v_pk_fma_f32 v[74:75], v[74:75], 0.5, v[190:191] op_sel_hi:[1,0,1]
	v_pk_fma_f32 v[72:73], v[72:73], 0.5, v[188:189] op_sel_hi:[1,0,1]
	v_mul_f32_e32 v77, v75, v75
	v_mul_f32_e32 v76, v73, v73
	v_pk_fma_f32 v[70:71], v[70:71], 0.5, v[186:187] op_sel_hi:[1,0,1]
	s_mov_b32 s88, 0x140000
	s_mov_b32 s89, 0
	v_lshl_add_u64 v[212:213], v[204:205], 0, s[88:89]
	global_load_dwordx4 v[176:179], v[212:213], off offset:16
	global_load_dwordx4 v[180:183], v[212:213], off
	global_load_dwordx4 v[184:187], v[212:213], off offset:528
	global_load_dwordx4 v[188:191], v[212:213], off offset:512
	v_fmac_f32_e32 v76, v72, v72
	v_fmac_f32_e32 v77, v74, v74
	v_add_f32_e32 v76, v76, v77
	v_mul_f32_e32 v77, v69, v69
	v_mul_f32_e32 v78, v71, v71
	v_fmac_f32_e32 v77, v68, v68
	v_fmac_f32_e32 v78, v70, v70
	v_add_f32_e32 v77, v77, v78
	v_add_f32_e32 v76, v76, v77
	v_add_f32_e32 v76, v90, v76
	global_store_dwordx4 v[86:87], v[72:75], off offset:512
	global_store_dwordx4 v[86:87], v[68:71], off offset:528
	s_nop 0
	v_cvt_pk_bf16_f32 v72, v72, v73
	v_cvt_pk_bf16_f32 v73, v74, v75
	v_cvt_pk_bf16_f32 v74, v68, v69
	ds_bpermute_b32 v68, v167, v76
	v_cvt_pk_bf16_f32 v75, v70, v71
	global_store_dwordx4 v[88:89], v[72:75], off offset:256
	s_waitcnt lgkmcnt(0)
	v_add_f32_e32 v68, v76, v68
	ds_bpermute_b32 v69, v166, v68
	s_and_saveexec_b64 s[4:5], s[36:37]
	s_cbranch_execz .LBB0_997
	v_readlane_b32 s2, v250, 11
	v_lshlrev_b64 v[70:71], 7, v[84:85]
	v_readlane_b32 s3, v250, 12
	s_lshl_b32 s6, s30, 2
	s_waitcnt lgkmcnt(0)
	v_add_f32_e32 v68, v68, v69
	v_lshl_add_u64 v[70:71], s[2:3], 0, v[70:71]
	v_readlane_b32 s2, v253, 17
	v_readlane_b32 s3, v253, 18
	v_lshl_add_u64 v[70:71], s[0:1], 2, v[70:71]
	s_mov_b32 s7, s3
	v_writelane_b32 v253, s2, 17
	v_lshl_add_u64 v[70:71], v[70:71], 0, s[6:7]
	global_store_dword v[70:71], v68, off
	v_writelane_b32 v253, s3, 18
.LBB0_997:
	s_or_b64 exec, exec, s[4:5]
	v_add_u32_e32 v68, 0x80, v146
	s_waitcnt lgkmcnt(0)
	v_ashrrev_i32_e32 v69, 31, v68
	v_readlane_b32 s2, v250, 9
	v_lshlrev_b64 v[70:71], 13, v[68:69]
	v_readlane_b32 s3, v250, 10
	s_nop 1
	v_lshl_add_u64 v[70:71], s[2:3], 0, v[70:71]
	v_lshl_add_u64 v[70:71], v[144:145], 2, v[70:71]
	v_readlane_b32 s2, v252, 15
	v_readlane_b32 s3, v252, 16
	s_waitcnt vmcnt(25)
	v_pk_fma_f32 v[60:61], v[60:61], 0.5, v[228:229] op_sel_hi:[1,0,1]
	v_pk_fma_f32 v[66:67], v[66:67], 0.5, v[234:235] op_sel_hi:[1,0,1]
	v_pk_fma_f32 v[64:65], v[64:65], 0.5, v[232:233] op_sel_hi:[1,0,1]
	v_mul_f32_e32 v73, v67, v67
	v_mul_f32_e32 v72, v65, v65
	v_pk_fma_f32 v[62:63], v[62:63], 0.5, v[230:231] op_sel_hi:[1,0,1]
	v_fmac_f32_e32 v72, v64, v64
	v_fmac_f32_e32 v73, v66, v66
	v_add_f32_e32 v72, v72, v73
	v_mul_f32_e32 v73, v61, v61
	v_mul_f32_e32 v74, v63, v63
	global_store_dwordx4 v[70:71], v[64:67], off
	global_store_dwordx4 v[70:71], v[60:63], off offset:16
	v_fmac_f32_e32 v73, v60, v60
	v_fmac_f32_e32 v74, v62, v62
	v_cvt_pk_bf16_f32 v64, v64, v65
	v_cvt_pk_bf16_f32 v65, v66, v67
	v_cvt_pk_bf16_f32 v66, v60, v61
	v_lshlrev_b64 v[60:61], 12, v[68:69]
	v_add_f32_e32 v73, v73, v74
	v_lshl_add_u64 v[60:61], s[2:3], 0, v[60:61]
	v_add_f32_e32 v74, v72, v73
	v_cvt_pk_bf16_f32 v67, v62, v63
	v_lshl_add_u64 v[72:73], v[144:145], 1, v[60:61]
	global_store_dwordx4 v[72:73], v[64:67], off
	s_waitcnt vmcnt(26)
	v_pk_fma_f32 v[52:53], v[52:53], 0.5, v[236:237] op_sel_hi:[1,0,1]
	v_pk_fma_f32 v[58:59], v[58:59], 0.5, v[242:243] op_sel_hi:[1,0,1]
	v_pk_fma_f32 v[56:57], v[56:57], 0.5, v[240:241] op_sel_hi:[1,0,1]
	v_mul_f32_e32 v61, v59, v59
	v_mul_f32_e32 v60, v57, v57
	v_pk_fma_f32 v[54:55], v[54:55], 0.5, v[238:239] op_sel_hi:[1,0,1]
	s_mov_b32 s88, 0x160000
	s_mov_b32 s89, 0
	v_lshl_add_u64 v[212:213], v[204:205], 0, s[88:89]
	global_load_dwordx4 v[228:231], v[212:213], off offset:16
	global_load_dwordx4 v[232:235], v[212:213], off
	global_load_dwordx4 v[236:239], v[212:213], off offset:528
	global_load_dwordx4 v[240:243], v[212:213], off offset:512
	v_fmac_f32_e32 v60, v56, v56
	v_fmac_f32_e32 v61, v58, v58
	v_add_f32_e32 v60, v60, v61
	v_mul_f32_e32 v61, v53, v53
	v_mul_f32_e32 v62, v55, v55
	v_fmac_f32_e32 v61, v52, v52
	v_fmac_f32_e32 v62, v54, v54
	v_add_f32_e32 v61, v61, v62
	v_add_f32_e32 v60, v60, v61
	v_add_f32_e32 v60, v74, v60
	global_store_dwordx4 v[70:71], v[56:59], off offset:512
	global_store_dwordx4 v[70:71], v[52:55], off offset:528
	s_nop 0
	v_cvt_pk_bf16_f32 v56, v56, v57
	v_cvt_pk_bf16_f32 v57, v58, v59
	v_cvt_pk_bf16_f32 v58, v52, v53
	ds_bpermute_b32 v52, v167, v60
	v_cvt_pk_bf16_f32 v59, v54, v55
	global_store_dwordx4 v[72:73], v[56:59], off offset:256
	s_waitcnt lgkmcnt(0)
	v_add_f32_e32 v52, v60, v52
	ds_bpermute_b32 v53, v166, v52
	s_and_saveexec_b64 s[4:5], s[36:37]
	s_cbranch_execz .LBB0_999
	v_readlane_b32 s2, v250, 11
	v_lshlrev_b64 v[54:55], 7, v[68:69]
	v_readlane_b32 s3, v250, 12
	s_lshl_b32 s6, s30, 2
	s_waitcnt lgkmcnt(0)
	v_add_f32_e32 v52, v52, v53
	v_lshl_add_u64 v[54:55], s[2:3], 0, v[54:55]
	v_readlane_b32 s2, v253, 17
	v_readlane_b32 s3, v253, 18
	v_lshl_add_u64 v[54:55], s[0:1], 2, v[54:55]
	s_mov_b32 s7, s3
	v_writelane_b32 v253, s2, 17
	v_lshl_add_u64 v[54:55], v[54:55], 0, s[6:7]
	global_store_dword v[54:55], v52, off
	v_writelane_b32 v253, s3, 18
.LBB0_999:
	s_or_b64 exec, exec, s[4:5]
	v_add_u32_e32 v52, 0x90, v146
	s_waitcnt lgkmcnt(0)
	v_ashrrev_i32_e32 v53, 31, v52
	v_readlane_b32 s2, v250, 9
	v_lshlrev_b64 v[54:55], 13, v[52:53]
	v_readlane_b32 s3, v250, 10
	s_nop 1
	v_lshl_add_u64 v[54:55], s[2:3], 0, v[54:55]
	v_lshl_add_u64 v[54:55], v[144:145], 2, v[54:55]
	v_readlane_b32 s2, v252, 15
	v_readlane_b32 s3, v252, 16
	s_waitcnt vmcnt(25)
	v_pk_fma_f32 v[44:45], v[44:45], 0.5, v[192:193] op_sel_hi:[1,0,1]
	v_pk_fma_f32 v[50:51], v[50:51], 0.5, v[198:199] op_sel_hi:[1,0,1]
	v_pk_fma_f32 v[48:49], v[48:49], 0.5, v[196:197] op_sel_hi:[1,0,1]
	v_mul_f32_e32 v57, v51, v51
	v_mul_f32_e32 v56, v49, v49
	v_pk_fma_f32 v[46:47], v[46:47], 0.5, v[194:195] op_sel_hi:[1,0,1]
	v_fmac_f32_e32 v56, v48, v48
	v_fmac_f32_e32 v57, v50, v50
	v_add_f32_e32 v56, v56, v57
	v_mul_f32_e32 v57, v45, v45
	v_mul_f32_e32 v58, v47, v47
	global_store_dwordx4 v[54:55], v[48:51], off
	global_store_dwordx4 v[54:55], v[44:47], off offset:16
	v_fmac_f32_e32 v57, v44, v44
	v_fmac_f32_e32 v58, v46, v46
	v_cvt_pk_bf16_f32 v48, v48, v49
	v_cvt_pk_bf16_f32 v49, v50, v51
	v_cvt_pk_bf16_f32 v50, v44, v45
	v_lshlrev_b64 v[44:45], 12, v[52:53]
	v_add_f32_e32 v57, v57, v58
	v_lshl_add_u64 v[44:45], s[2:3], 0, v[44:45]
	v_add_f32_e32 v58, v56, v57
	v_cvt_pk_bf16_f32 v51, v46, v47
	v_lshl_add_u64 v[56:57], v[144:145], 1, v[44:45]
	global_store_dwordx4 v[56:57], v[48:51], off
	s_waitcnt vmcnt(26)
	v_pk_fma_f32 v[36:37], v[36:37], 0.5, v[200:201] op_sel_hi:[1,0,1]
	v_pk_fma_f32 v[42:43], v[42:43], 0.5, v[246:247] op_sel_hi:[1,0,1]
	v_pk_fma_f32 v[40:41], v[40:41], 0.5, v[244:245] op_sel_hi:[1,0,1]
	v_mul_f32_e32 v45, v43, v43
	v_mul_f32_e32 v44, v41, v41
	v_pk_fma_f32 v[38:39], v[38:39], 0.5, v[202:203] op_sel_hi:[1,0,1]
	v_fmac_f32_e32 v44, v40, v40
	v_fmac_f32_e32 v45, v42, v42
	v_add_f32_e32 v44, v44, v45
	v_mul_f32_e32 v45, v37, v37
	v_mul_f32_e32 v46, v39, v39
	v_fmac_f32_e32 v45, v36, v36
	v_fmac_f32_e32 v46, v38, v38
	v_add_f32_e32 v45, v45, v46
	v_add_f32_e32 v44, v44, v45
	v_add_f32_e32 v44, v58, v44
	global_store_dwordx4 v[54:55], v[40:43], off offset:512
	global_store_dwordx4 v[54:55], v[36:39], off offset:528
	s_nop 0
	v_cvt_pk_bf16_f32 v40, v40, v41
	v_cvt_pk_bf16_f32 v41, v42, v43
	v_cvt_pk_bf16_f32 v42, v36, v37
	ds_bpermute_b32 v36, v167, v44
	v_cvt_pk_bf16_f32 v43, v38, v39
	global_store_dwordx4 v[56:57], v[40:43], off offset:256
	s_waitcnt lgkmcnt(0)
	v_add_f32_e32 v36, v44, v36
	ds_bpermute_b32 v37, v166, v36
	s_and_saveexec_b64 s[4:5], s[36:37]
	s_cbranch_execz .LBB0_1001
	v_readlane_b32 s2, v250, 11
	v_lshlrev_b64 v[38:39], 7, v[52:53]
	v_readlane_b32 s3, v250, 12
	s_lshl_b32 s6, s30, 2
	s_waitcnt lgkmcnt(0)
	v_add_f32_e32 v36, v36, v37
	v_lshl_add_u64 v[38:39], s[2:3], 0, v[38:39]
	v_readlane_b32 s2, v253, 17
	v_readlane_b32 s3, v253, 18
	v_lshl_add_u64 v[38:39], s[0:1], 2, v[38:39]
	s_mov_b32 s7, s3
	v_writelane_b32 v253, s2, 17
	v_lshl_add_u64 v[38:39], v[38:39], 0, s[6:7]
	global_store_dword v[38:39], v36, off
	v_writelane_b32 v253, s3, 18
.LBB0_1001:
	s_or_b64 exec, exec, s[4:5]
	v_add_u32_e32 v36, 0xa0, v146
	s_waitcnt lgkmcnt(0)
	v_ashrrev_i32_e32 v37, 31, v36
	v_readlane_b32 s2, v250, 9
	v_lshlrev_b64 v[38:39], 13, v[36:37]
	v_readlane_b32 s3, v250, 10
	s_nop 1
	v_lshl_add_u64 v[38:39], s[2:3], 0, v[38:39]
	v_lshl_add_u64 v[38:39], v[144:145], 2, v[38:39]
	v_readlane_b32 s2, v252, 15
	v_readlane_b32 s3, v252, 16
	s_waitcnt vmcnt(21)
	v_pk_fma_f32 v[28:29], v[28:29], 0.5, v[176:177] op_sel_hi:[1,0,1]
	v_pk_fma_f32 v[34:35], v[34:35], 0.5, v[182:183] op_sel_hi:[1,0,1]
	v_pk_fma_f32 v[32:33], v[32:33], 0.5, v[180:181] op_sel_hi:[1,0,1]
	v_mul_f32_e32 v41, v35, v35
	v_mul_f32_e32 v40, v33, v33
	v_pk_fma_f32 v[30:31], v[30:31], 0.5, v[178:179] op_sel_hi:[1,0,1]
	v_fmac_f32_e32 v40, v32, v32
	v_fmac_f32_e32 v41, v34, v34
	v_add_f32_e32 v40, v40, v41
	v_mul_f32_e32 v41, v29, v29
	v_mul_f32_e32 v42, v31, v31
	global_store_dwordx4 v[38:39], v[32:35], off
	global_store_dwordx4 v[38:39], v[28:31], off offset:16
	v_fmac_f32_e32 v41, v28, v28
	v_fmac_f32_e32 v42, v30, v30
	v_cvt_pk_bf16_f32 v32, v32, v33
	v_cvt_pk_bf16_f32 v33, v34, v35
	v_cvt_pk_bf16_f32 v34, v28, v29
	v_lshlrev_b64 v[28:29], 12, v[36:37]
	v_add_f32_e32 v41, v41, v42
	v_lshl_add_u64 v[28:29], s[2:3], 0, v[28:29]
	v_add_f32_e32 v42, v40, v41
	v_cvt_pk_bf16_f32 v35, v30, v31
	v_lshl_add_u64 v[40:41], v[144:145], 1, v[28:29]
	global_store_dwordx4 v[40:41], v[32:35], off
	s_waitcnt vmcnt(22)
	v_pk_fma_f32 v[20:21], v[20:21], 0.5, v[184:185] op_sel_hi:[1,0,1]
	v_pk_fma_f32 v[26:27], v[26:27], 0.5, v[190:191] op_sel_hi:[1,0,1]
	v_pk_fma_f32 v[24:25], v[24:25], 0.5, v[188:189] op_sel_hi:[1,0,1]
	v_mul_f32_e32 v29, v27, v27
	v_mul_f32_e32 v28, v25, v25
	v_pk_fma_f32 v[22:23], v[22:23], 0.5, v[186:187] op_sel_hi:[1,0,1]
	v_fmac_f32_e32 v28, v24, v24
	v_fmac_f32_e32 v29, v26, v26
	v_add_f32_e32 v28, v28, v29
	v_mul_f32_e32 v29, v21, v21
	v_mul_f32_e32 v30, v23, v23
	v_fmac_f32_e32 v29, v20, v20
	v_fmac_f32_e32 v30, v22, v22
	v_add_f32_e32 v29, v29, v30
	v_add_f32_e32 v28, v28, v29
	v_add_f32_e32 v28, v42, v28
	global_store_dwordx4 v[38:39], v[24:27], off offset:512
	global_store_dwordx4 v[38:39], v[20:23], off offset:528
	s_nop 0
	v_cvt_pk_bf16_f32 v24, v24, v25
	v_cvt_pk_bf16_f32 v25, v26, v27
	v_cvt_pk_bf16_f32 v26, v20, v21
	ds_bpermute_b32 v20, v167, v28
	v_cvt_pk_bf16_f32 v27, v22, v23
	global_store_dwordx4 v[40:41], v[24:27], off offset:256
	s_waitcnt lgkmcnt(0)
	v_add_f32_e32 v20, v28, v20
	ds_bpermute_b32 v21, v166, v20
	s_and_saveexec_b64 s[4:5], s[36:37]
	s_cbranch_execz .LBB0_1003
	v_readlane_b32 s2, v250, 11
	v_lshlrev_b64 v[22:23], 7, v[36:37]
	v_readlane_b32 s3, v250, 12
	s_lshl_b32 s6, s30, 2
	s_waitcnt lgkmcnt(0)
	v_add_f32_e32 v20, v20, v21
	v_lshl_add_u64 v[22:23], s[2:3], 0, v[22:23]
	v_readlane_b32 s2, v253, 17
	v_readlane_b32 s3, v253, 18
	v_lshl_add_u64 v[22:23], s[0:1], 2, v[22:23]
	s_mov_b32 s7, s3
	v_writelane_b32 v253, s2, 17
	v_lshl_add_u64 v[22:23], v[22:23], 0, s[6:7]
	global_store_dword v[22:23], v20, off
	v_writelane_b32 v253, s3, 18
.LBB0_1003:
	s_or_b64 exec, exec, s[4:5]
	v_add_u32_e32 v20, 0xb0, v146
	s_waitcnt lgkmcnt(0)
	v_ashrrev_i32_e32 v21, 31, v20
	v_readlane_b32 s2, v250, 9
	v_lshlrev_b64 v[22:23], 13, v[20:21]
	v_readlane_b32 s3, v250, 10
	s_nop 1
	v_lshl_add_u64 v[22:23], s[2:3], 0, v[22:23]
	v_lshl_add_u64 v[22:23], v[144:145], 2, v[22:23]
	v_readlane_b32 s2, v252, 15
	v_readlane_b32 s3, v252, 16
	s_waitcnt vmcnt(17)
	v_pk_fma_f32 v[12:13], v[12:13], 0.5, v[228:229] op_sel_hi:[1,0,1]
	v_pk_fma_f32 v[18:19], v[18:19], 0.5, v[234:235] op_sel_hi:[1,0,1]
	v_pk_fma_f32 v[16:17], v[16:17], 0.5, v[232:233] op_sel_hi:[1,0,1]
	v_mul_f32_e32 v25, v19, v19
	v_mul_f32_e32 v24, v17, v17
	v_pk_fma_f32 v[14:15], v[14:15], 0.5, v[230:231] op_sel_hi:[1,0,1]
	v_fmac_f32_e32 v24, v16, v16
	v_fmac_f32_e32 v25, v18, v18
	v_add_f32_e32 v24, v24, v25
	v_mul_f32_e32 v25, v13, v13
	v_mul_f32_e32 v26, v15, v15
	global_store_dwordx4 v[22:23], v[16:19], off
	global_store_dwordx4 v[22:23], v[12:15], off offset:16
	v_fmac_f32_e32 v25, v12, v12
	v_fmac_f32_e32 v26, v14, v14
	v_cvt_pk_bf16_f32 v16, v16, v17
	v_cvt_pk_bf16_f32 v17, v18, v19
	v_cvt_pk_bf16_f32 v18, v12, v13
	v_lshlrev_b64 v[12:13], 12, v[20:21]
	v_add_f32_e32 v25, v25, v26
	v_lshl_add_u64 v[12:13], s[2:3], 0, v[12:13]
	v_add_f32_e32 v26, v24, v25
	v_cvt_pk_bf16_f32 v19, v14, v15
	v_lshl_add_u64 v[24:25], v[144:145], 1, v[12:13]
	global_store_dwordx4 v[24:25], v[16:19], off
	s_waitcnt vmcnt(18)
	v_pk_fma_f32 v[2:3], v[2:3], 0.5, v[236:237] op_sel_hi:[1,0,1]
	v_pk_fma_f32 v[8:9], v[8:9], 0.5, v[242:243] op_sel_hi:[1,0,1]
	v_pk_fma_f32 v[6:7], v[6:7], 0.5, v[240:241] op_sel_hi:[1,0,1]
	v_mul_f32_e32 v13, v9, v9
	v_mul_f32_e32 v12, v7, v7
	v_pk_fma_f32 v[4:5], v[4:5], 0.5, v[238:239] op_sel_hi:[1,0,1]
	v_fmac_f32_e32 v12, v6, v6
	v_fmac_f32_e32 v13, v8, v8
	v_add_f32_e32 v12, v12, v13
	v_mul_f32_e32 v13, v3, v3
	v_mul_f32_e32 v14, v5, v5
	v_fmac_f32_e32 v13, v2, v2
	v_fmac_f32_e32 v14, v4, v4
	v_add_f32_e32 v13, v13, v14
	v_add_f32_e32 v12, v12, v13
	v_add_f32_e32 v12, v26, v12
	global_store_dwordx4 v[22:23], v[6:9], off offset:512
	global_store_dwordx4 v[22:23], v[2:5], off offset:528
	s_nop 0
	v_cvt_pk_bf16_f32 v6, v6, v7
	v_cvt_pk_bf16_f32 v7, v8, v9
	v_cvt_pk_bf16_f32 v8, v2, v3
	ds_bpermute_b32 v2, v167, v12
	v_cvt_pk_bf16_f32 v9, v4, v5
	global_store_dwordx4 v[24:25], v[6:9], off offset:256
	s_waitcnt lgkmcnt(0)
	v_add_f32_e32 v2, v12, v2
	ds_bpermute_b32 v3, v166, v2
	s_and_saveexec_b64 s[4:5], s[36:37]
	s_cbranch_execz .LBB0_1005
	v_readlane_b32 s2, v250, 11
	v_lshlrev_b64 v[4:5], 7, v[20:21]
	v_readlane_b32 s3, v250, 12
	s_waitcnt lgkmcnt(0)
	v_add_f32_e32 v2, v2, v3
	v_lshl_add_u64 v[4:5], s[2:3], 0, v[4:5]
	v_lshl_add_u64 v[4:5], s[0:1], 2, v[4:5]
	v_readlane_b32 s0, v253, 17
	v_readlane_b32 s1, v253, 18
	s_mov_b32 s3, s1
	s_lshl_b32 s2, s30, 2
	v_writelane_b32 v253, s0, 17
	v_lshl_add_u64 v[4:5], v[4:5], 0, s[2:3]
	global_store_dword v[4:5], v2, off
	v_writelane_b32 v253, s1, 18

.LBB0_2860:
	v_and_b32_e32 v148, 64, v153
	v_xor_b32_e32 v147, 16, v153
	v_add_u32_e32 v148, 64, v148
	v_cmp_lt_i32_e32 vcc, v147, v148
	v_lshl_add_u32 v146, s25, 8, v1
	v_readlane_b32 s2, v250, 9
	v_cndmask_b32_e32 v147, v153, v147, vcc
	v_lshlrev_b32_e32 v167, 2, v147
	v_xor_b32_e32 v147, 32, v153
	v_cmp_lt_i32_e32 vcc, v147, v148
	v_lshl_or_b32 v144, s23, 8, v151
	v_readlane_b32 s3, v250, 10
	v_cndmask_b32_e32 v147, v153, v147, vcc
	v_lshlrev_b32_e32 v166, 2, v147
	v_ashrrev_i32_e32 v147, 31, v146
	v_lshlrev_b64 v[148:149], 13, v[146:147]
	v_ashrrev_i32_e32 v145, 31, v144
	v_lshl_add_u64 v[148:149], s[2:3], 0, v[148:149]
	v_lshl_add_u64 v[148:149], v[144:145], 2, v[148:149]
	v_mov_b32_e32 v204, v148
	v_mov_b32_e32 v205, v149
	global_load_dwordx4 v[176:179], v[148:149], off offset:16
	global_load_dwordx4 v[180:183], v[148:149], off
	global_load_dwordx4 v[184:187], v[148:149], off offset:528
	global_load_dwordx4 v[188:191], v[148:149], off offset:512
	s_mov_b32 s88, 0x20000
	s_mov_b32 s89, 0
	v_lshl_add_u64 v[212:213], v[204:205], 0, s[88:89]
	global_load_dwordx4 v[228:231], v[212:213], off offset:16
	global_load_dwordx4 v[232:235], v[212:213], off
	global_load_dwordx4 v[236:239], v[212:213], off offset:528
	global_load_dwordx4 v[240:243], v[212:213], off offset:512
	s_mov_b32 s88, 0x40000
	s_mov_b32 s89, 0
	v_lshl_add_u64 v[214:215], v[204:205], 0, s[88:89]
	global_load_dwordx4 v[192:195], v[214:215], off offset:16
	global_load_dwordx4 v[196:199], v[214:215], off
	global_load_dwordx4 v[200:203], v[214:215], off offset:528
	global_load_dwordx4 v[244:247], v[214:215], off offset:512
	v_readlane_b32 s2, v252, 15
	v_readlane_b32 s3, v252, 16
	s_lshl_b32 s0, s23, 2
	s_ashr_i32 s1, s0, 31
	s_waitcnt vmcnt(10)
	v_pk_add_f32 v[124:125], v[124:125], v[176:177]
	v_pk_add_f32 v[130:131], v[130:131], v[182:183]
	v_pk_add_f32 v[128:129], v[128:129], v[180:181]
	v_mul_f32_e32 v169, v131, v131
	v_mul_f32_e32 v168, v129, v129
	v_pk_add_f32 v[126:127], v[126:127], v[178:179]
	v_fmac_f32_e32 v168, v128, v128
	v_fmac_f32_e32 v169, v130, v130
	v_add_f32_e32 v168, v168, v169
	v_mul_f32_e32 v169, v125, v125
	v_mul_f32_e32 v170, v127, v127
	global_store_dwordx4 v[148:149], v[128:131], off
	global_store_dwordx4 v[148:149], v[124:127], off offset:16
	v_fmac_f32_e32 v169, v124, v124
	v_fmac_f32_e32 v170, v126, v126
	v_cvt_pk_bf16_f32 v128, v128, v129
	v_cvt_pk_bf16_f32 v129, v130, v131
	v_cvt_pk_bf16_f32 v130, v124, v125
	v_lshlrev_b64 v[124:125], 12, v[146:147]
	v_add_f32_e32 v169, v169, v170
	v_lshl_add_u64 v[124:125], s[2:3], 0, v[124:125]
	v_add_f32_e32 v170, v168, v169
	v_cvt_pk_bf16_f32 v131, v126, v127
	v_lshl_add_u64 v[168:169], v[144:145], 1, v[124:125]
	global_store_dwordx4 v[168:169], v[128:131], off
	s_waitcnt vmcnt(11)
	v_pk_add_f32 v[116:117], v[116:117], v[184:185]
	v_pk_add_f32 v[122:123], v[122:123], v[190:191]
	v_pk_add_f32 v[120:121], v[120:121], v[188:189]
	v_mul_f32_e32 v125, v123, v123
	v_mul_f32_e32 v124, v121, v121
	v_pk_add_f32 v[118:119], v[118:119], v[186:187]
	s_mov_b32 s88, 0x60000
	s_mov_b32 s89, 0
	v_lshl_add_u64 v[212:213], v[204:205], 0, s[88:89]
	global_load_dwordx4 v[176:179], v[212:213], off offset:16
	global_load_dwordx4 v[180:183], v[212:213], off
	global_load_dwordx4 v[184:187], v[212:213], off offset:528
	global_load_dwordx4 v[188:191], v[212:213], off offset:512
	v_fmac_f32_e32 v124, v120, v120
	v_fmac_f32_e32 v125, v122, v122
	v_add_f32_e32 v124, v124, v125
	v_mul_f32_e32 v125, v117, v117
	v_mul_f32_e32 v126, v119, v119
	v_fmac_f32_e32 v125, v116, v116
	v_fmac_f32_e32 v126, v118, v118
	v_add_f32_e32 v125, v125, v126
	v_add_f32_e32 v124, v124, v125
	v_add_f32_e32 v124, v170, v124
	global_store_dwordx4 v[148:149], v[120:123], off offset:512
	global_store_dwordx4 v[148:149], v[116:119], off offset:528
	s_nop 0
	v_cvt_pk_bf16_f32 v120, v120, v121
	v_cvt_pk_bf16_f32 v121, v122, v123
	v_cvt_pk_bf16_f32 v122, v116, v117
	ds_bpermute_b32 v116, v167, v124
	v_cvt_pk_bf16_f32 v123, v118, v119
	global_store_dwordx4 v[168:169], v[120:123], off offset:256
	s_waitcnt lgkmcnt(0)
	v_add_f32_e32 v116, v124, v116
	ds_bpermute_b32 v117, v166, v116
	s_and_saveexec_b64 s[4:5], s[36:37]
	s_cbranch_execz .LBB0_2862
	v_readlane_b32 s2, v250, 11
	v_lshlrev_b64 v[118:119], 7, v[146:147]
	v_readlane_b32 s3, v250, 12
	s_lshl_b32 s6, s56, 2
	s_waitcnt lgkmcnt(0)
	v_add_f32_e32 v116, v116, v117
	v_lshl_add_u64 v[118:119], s[2:3], 0, v[118:119]
	v_readlane_b32 s2, v253, 17
	v_readlane_b32 s3, v253, 18
	v_lshl_add_u64 v[118:119], s[0:1], 2, v[118:119]
	s_mov_b32 s7, s3
	v_writelane_b32 v253, s2, 17
	v_lshl_add_u64 v[118:119], v[118:119], 0, s[6:7]
	global_store_dword v[118:119], v116, off
	v_writelane_b32 v253, s3, 18
.LBB0_2862:
	s_or_b64 exec, exec, s[4:5]
	v_or_b32_e32 v116, 16, v146
	s_waitcnt lgkmcnt(0)
	v_ashrrev_i32_e32 v117, 31, v116
	v_readlane_b32 s2, v250, 9
	v_lshlrev_b64 v[118:119], 13, v[116:117]
	v_readlane_b32 s3, v250, 10
	s_nop 1
	v_lshl_add_u64 v[118:119], s[2:3], 0, v[118:119]
	v_lshl_add_u64 v[118:119], v[144:145], 2, v[118:119]
	v_readlane_b32 s2, v252, 15
	v_readlane_b32 s3, v252, 16
	s_waitcnt vmcnt(16)
	v_pk_add_f32 v[108:109], v[108:109], v[228:229]
	v_pk_add_f32 v[114:115], v[114:115], v[234:235]
	v_pk_add_f32 v[112:113], v[112:113], v[232:233]
	v_mul_f32_e32 v121, v115, v115
	v_mul_f32_e32 v120, v113, v113
	v_pk_add_f32 v[110:111], v[110:111], v[230:231]
	v_fmac_f32_e32 v120, v112, v112
	v_fmac_f32_e32 v121, v114, v114
	v_add_f32_e32 v120, v120, v121
	v_mul_f32_e32 v121, v109, v109
	v_mul_f32_e32 v122, v111, v111
	global_store_dwordx4 v[118:119], v[112:115], off
	global_store_dwordx4 v[118:119], v[108:111], off offset:16
	v_fmac_f32_e32 v121, v108, v108
	v_fmac_f32_e32 v122, v110, v110
	v_cvt_pk_bf16_f32 v112, v112, v113
	v_cvt_pk_bf16_f32 v113, v114, v115
	v_cvt_pk_bf16_f32 v114, v108, v109
	v_lshlrev_b64 v[108:109], 12, v[116:117]
	v_add_f32_e32 v121, v121, v122
	v_lshl_add_u64 v[108:109], s[2:3], 0, v[108:109]
	v_add_f32_e32 v122, v120, v121
	v_cvt_pk_bf16_f32 v115, v110, v111
	v_lshl_add_u64 v[120:121], v[144:145], 1, v[108:109]
	global_store_dwordx4 v[120:121], v[112:115], off
	s_waitcnt vmcnt(17)
	v_pk_add_f32 v[100:101], v[100:101], v[236:237]
	v_pk_add_f32 v[106:107], v[106:107], v[242:243]
	v_pk_add_f32 v[104:105], v[104:105], v[240:241]
	v_mul_f32_e32 v109, v107, v107
	v_mul_f32_e32 v108, v105, v105
	v_pk_add_f32 v[102:103], v[102:103], v[238:239]
	s_mov_b32 s88, 0x100000
	s_mov_b32 s89, 0
	v_lshl_add_u64 v[212:213], v[204:205], 0, s[88:89]
	global_load_dwordx4 v[228:231], v[212:213], off offset:16
	global_load_dwordx4 v[232:235], v[212:213], off
	global_load_dwordx4 v[236:239], v[212:213], off offset:528
	global_load_dwordx4 v[240:243], v[212:213], off offset:512
	v_fmac_f32_e32 v108, v104, v104
	v_fmac_f32_e32 v109, v106, v106
	v_add_f32_e32 v108, v108, v109
	v_mul_f32_e32 v109, v101, v101
	v_mul_f32_e32 v110, v103, v103
	v_fmac_f32_e32 v109, v100, v100
	v_fmac_f32_e32 v110, v102, v102
	v_add_f32_e32 v109, v109, v110
	v_add_f32_e32 v108, v108, v109
	v_add_f32_e32 v108, v122, v108
	global_store_dwordx4 v[118:119], v[104:107], off offset:512
	global_store_dwordx4 v[118:119], v[100:103], off offset:528
	s_nop 0
	v_cvt_pk_bf16_f32 v104, v104, v105
	v_cvt_pk_bf16_f32 v105, v106, v107
	v_cvt_pk_bf16_f32 v106, v100, v101
	ds_bpermute_b32 v100, v167, v108
	v_cvt_pk_bf16_f32 v107, v102, v103
	global_store_dwordx4 v[120:121], v[104:107], off offset:256
	s_waitcnt lgkmcnt(0)
	v_add_f32_e32 v100, v108, v100
	ds_bpermute_b32 v101, v166, v100
	s_and_saveexec_b64 s[4:5], s[36:37]
	s_cbranch_execz .LBB0_2864
	v_readlane_b32 s2, v250, 11
	v_lshlrev_b64 v[102:103], 7, v[116:117]
	v_readlane_b32 s3, v250, 12
	s_lshl_b32 s6, s56, 2
	s_waitcnt lgkmcnt(0)
	v_add_f32_e32 v100, v100, v101
	v_lshl_add_u64 v[102:103], s[2:3], 0, v[102:103]
	v_readlane_b32 s2, v253, 17
	v_readlane_b32 s3, v253, 18
	v_lshl_add_u64 v[102:103], s[0:1], 2, v[102:103]
	s_mov_b32 s7, s3
	v_writelane_b32 v253, s2, 17
	v_lshl_add_u64 v[102:103], v[102:103], 0, s[6:7]
	global_store_dword v[102:103], v100, off
	v_writelane_b32 v253, s3, 18
.LBB0_2864:
	s_or_b64 exec, exec, s[4:5]
	v_or_b32_e32 v100, 32, v146
	s_waitcnt lgkmcnt(0)
	v_ashrrev_i32_e32 v101, 31, v100
	v_readlane_b32 s2, v250, 9
	v_lshlrev_b64 v[102:103], 13, v[100:101]
	v_readlane_b32 s3, v250, 10
	s_nop 1
	v_lshl_add_u64 v[102:103], s[2:3], 0, v[102:103]
	v_lshl_add_u64 v[102:103], v[144:145], 2, v[102:103]
	v_readlane_b32 s2, v252, 15
	v_readlane_b32 s3, v252, 16
	s_waitcnt vmcnt(22)
	v_pk_add_f32 v[92:93], v[92:93], v[192:193]
	v_pk_add_f32 v[98:99], v[98:99], v[198:199]
	v_pk_add_f32 v[96:97], v[96:97], v[196:197]
	v_mul_f32_e32 v105, v99, v99
	v_mul_f32_e32 v104, v97, v97
	v_pk_add_f32 v[94:95], v[94:95], v[194:195]
	v_fmac_f32_e32 v104, v96, v96
	v_fmac_f32_e32 v105, v98, v98
	v_add_f32_e32 v104, v104, v105
	v_mul_f32_e32 v105, v93, v93
	v_mul_f32_e32 v106, v95, v95
	global_store_dwordx4 v[102:103], v[96:99], off
	global_store_dwordx4 v[102:103], v[92:95], off offset:16
	v_fmac_f32_e32 v105, v92, v92
	v_fmac_f32_e32 v106, v94, v94
	v_cvt_pk_bf16_f32 v96, v96, v97
	v_cvt_pk_bf16_f32 v97, v98, v99
	v_cvt_pk_bf16_f32 v98, v92, v93
	v_lshlrev_b64 v[92:93], 12, v[100:101]
	v_add_f32_e32 v105, v105, v106
	v_lshl_add_u64 v[92:93], s[2:3], 0, v[92:93]
	v_add_f32_e32 v106, v104, v105
	v_cvt_pk_bf16_f32 v99, v94, v95
	v_lshl_add_u64 v[104:105], v[144:145], 1, v[92:93]
	global_store_dwordx4 v[104:105], v[96:99], off
	s_waitcnt vmcnt(23)
	v_pk_add_f32 v[84:85], v[84:85], v[200:201]
	v_pk_add_f32 v[90:91], v[90:91], v[246:247]
	v_pk_add_f32 v[88:89], v[88:89], v[244:245]
	v_mul_f32_e32 v93, v91, v91
	v_mul_f32_e32 v92, v89, v89
	v_pk_add_f32 v[86:87], v[86:87], v[202:203]
	s_mov_b32 s88, 0x120000
	s_mov_b32 s89, 0
	v_lshl_add_u64 v[212:213], v[204:205], 0, s[88:89]
	global_load_dwordx4 v[192:195], v[212:213], off offset:16
	global_load_dwordx4 v[196:199], v[212:213], off
	global_load_dwordx4 v[200:203], v[212:213], off offset:528
	global_load_dwordx4 v[244:247], v[212:213], off offset:512
	v_fmac_f32_e32 v92, v88, v88
	v_fmac_f32_e32 v93, v90, v90
	v_add_f32_e32 v92, v92, v93
	v_mul_f32_e32 v93, v85, v85
	v_mul_f32_e32 v94, v87, v87
	v_fmac_f32_e32 v93, v84, v84
	v_fmac_f32_e32 v94, v86, v86
	v_add_f32_e32 v93, v93, v94
	v_add_f32_e32 v92, v92, v93
	v_add_f32_e32 v92, v106, v92
	global_store_dwordx4 v[102:103], v[88:91], off offset:512
	global_store_dwordx4 v[102:103], v[84:87], off offset:528
	s_nop 0
	v_cvt_pk_bf16_f32 v88, v88, v89
	v_cvt_pk_bf16_f32 v89, v90, v91
	v_cvt_pk_bf16_f32 v90, v84, v85
	ds_bpermute_b32 v84, v167, v92
	v_cvt_pk_bf16_f32 v91, v86, v87
	global_store_dwordx4 v[104:105], v[88:91], off offset:256
	s_waitcnt lgkmcnt(0)
	v_add_f32_e32 v84, v92, v84
	ds_bpermute_b32 v85, v166, v84
	s_and_saveexec_b64 s[4:5], s[36:37]
	s_cbranch_execz .LBB0_2866
	v_readlane_b32 s2, v250, 11
	v_lshlrev_b64 v[86:87], 7, v[100:101]
	v_readlane_b32 s3, v250, 12
	s_lshl_b32 s6, s56, 2
	s_waitcnt lgkmcnt(0)
	v_add_f32_e32 v84, v84, v85
	v_lshl_add_u64 v[86:87], s[2:3], 0, v[86:87]
	v_readlane_b32 s2, v253, 17
	v_readlane_b32 s3, v253, 18
	v_lshl_add_u64 v[86:87], s[0:1], 2, v[86:87]
	s_mov_b32 s7, s3
	v_writelane_b32 v253, s2, 17
	v_lshl_add_u64 v[86:87], v[86:87], 0, s[6:7]
	global_store_dword v[86:87], v84, off
	v_writelane_b32 v253, s3, 18
.LBB0_2866:
	s_or_b64 exec, exec, s[4:5]
	v_or_b32_e32 v84, 48, v146
	s_waitcnt lgkmcnt(0)
	v_ashrrev_i32_e32 v85, 31, v84
	v_readlane_b32 s2, v250, 9
	v_lshlrev_b64 v[86:87], 13, v[84:85]
	v_readlane_b32 s3, v250, 10
	s_nop 1
	v_lshl_add_u64 v[86:87], s[2:3], 0, v[86:87]
	v_lshl_add_u64 v[86:87], v[144:145], 2, v[86:87]
	v_readlane_b32 s2, v252, 15
	v_readlane_b32 s3, v252, 16
	s_waitcnt vmcnt(25)
	v_pk_add_f32 v[76:77], v[76:77], v[176:177]
	v_pk_add_f32 v[82:83], v[82:83], v[182:183]
	v_pk_add_f32 v[80:81], v[80:81], v[180:181]
	v_mul_f32_e32 v89, v83, v83
	v_mul_f32_e32 v88, v81, v81
	v_pk_add_f32 v[78:79], v[78:79], v[178:179]
	v_fmac_f32_e32 v88, v80, v80
	v_fmac_f32_e32 v89, v82, v82
	v_add_f32_e32 v88, v88, v89
	v_mul_f32_e32 v89, v77, v77
	v_mul_f32_e32 v90, v79, v79
	global_store_dwordx4 v[86:87], v[80:83], off
	global_store_dwordx4 v[86:87], v[76:79], off offset:16
	v_fmac_f32_e32 v89, v76, v76
	v_fmac_f32_e32 v90, v78, v78
	v_cvt_pk_bf16_f32 v80, v80, v81
	v_cvt_pk_bf16_f32 v81, v82, v83
	v_cvt_pk_bf16_f32 v82, v76, v77
	v_lshlrev_b64 v[76:77], 12, v[84:85]
	v_add_f32_e32 v89, v89, v90
	v_lshl_add_u64 v[76:77], s[2:3], 0, v[76:77]
	v_add_f32_e32 v90, v88, v89
	v_cvt_pk_bf16_f32 v83, v78, v79
	v_lshl_add_u64 v[88:89], v[144:145], 1, v[76:77]
	global_store_dwordx4 v[88:89], v[80:83], off
	s_waitcnt vmcnt(26)
	v_pk_add_f32 v[68:69], v[68:69], v[184:185]
	v_pk_add_f32 v[74:75], v[74:75], v[190:191]
	v_pk_add_f32 v[72:73], v[72:73], v[188:189]
	v_mul_f32_e32 v77, v75, v75
	v_mul_f32_e32 v76, v73, v73
	v_pk_add_f32 v[70:71], v[70:71], v[186:187]
	s_mov_b32 s88, 0x140000
	s_mov_b32 s89, 0
	v_lshl_add_u64 v[212:213], v[204:205], 0, s[88:89]
	global_load_dwordx4 v[176:179], v[212:213], off offset:16
	global_load_dwordx4 v[180:183], v[212:213], off
	global_load_dwordx4 v[184:187], v[212:213], off offset:528
	global_load_dwordx4 v[188:191], v[212:213], off offset:512
	v_fmac_f32_e32 v76, v72, v72
	v_fmac_f32_e32 v77, v74, v74
	v_add_f32_e32 v76, v76, v77
	v_mul_f32_e32 v77, v69, v69
	v_mul_f32_e32 v78, v71, v71
	v_fmac_f32_e32 v77, v68, v68
	v_fmac_f32_e32 v78, v70, v70
	v_add_f32_e32 v77, v77, v78
	v_add_f32_e32 v76, v76, v77
	v_add_f32_e32 v76, v90, v76
	global_store_dwordx4 v[86:87], v[72:75], off offset:512
	global_store_dwordx4 v[86:87], v[68:71], off offset:528
	s_nop 0
	v_cvt_pk_bf16_f32 v72, v72, v73
	v_cvt_pk_bf16_f32 v73, v74, v75
	v_cvt_pk_bf16_f32 v74, v68, v69
	ds_bpermute_b32 v68, v167, v76
	v_cvt_pk_bf16_f32 v75, v70, v71
	global_store_dwordx4 v[88:89], v[72:75], off offset:256
	s_waitcnt lgkmcnt(0)
	v_add_f32_e32 v68, v76, v68
	ds_bpermute_b32 v69, v166, v68
	s_and_saveexec_b64 s[4:5], s[36:37]
	s_cbranch_execz .LBB0_2868
	v_readlane_b32 s2, v250, 11
	v_lshlrev_b64 v[70:71], 7, v[84:85]
	v_readlane_b32 s3, v250, 12
	s_lshl_b32 s6, s56, 2
	s_waitcnt lgkmcnt(0)
	v_add_f32_e32 v68, v68, v69
	v_lshl_add_u64 v[70:71], s[2:3], 0, v[70:71]
	v_readlane_b32 s2, v253, 17
	v_readlane_b32 s3, v253, 18
	v_lshl_add_u64 v[70:71], s[0:1], 2, v[70:71]
	s_mov_b32 s7, s3
	v_writelane_b32 v253, s2, 17
	v_lshl_add_u64 v[70:71], v[70:71], 0, s[6:7]
	global_store_dword v[70:71], v68, off
	v_writelane_b32 v253, s3, 18
.LBB0_2868:
	s_or_b64 exec, exec, s[4:5]
	v_add_u32_e32 v68, 0x80, v146
	s_waitcnt lgkmcnt(0)
	v_ashrrev_i32_e32 v69, 31, v68
	v_readlane_b32 s2, v250, 9
	v_lshlrev_b64 v[70:71], 13, v[68:69]
	v_readlane_b32 s3, v250, 10
	s_nop 1
	v_lshl_add_u64 v[70:71], s[2:3], 0, v[70:71]
	v_lshl_add_u64 v[70:71], v[144:145], 2, v[70:71]
	v_readlane_b32 s2, v252, 15
	v_readlane_b32 s3, v252, 16
	s_waitcnt vmcnt(25)
	v_pk_add_f32 v[60:61], v[60:61], v[228:229]
	v_pk_add_f32 v[66:67], v[66:67], v[234:235]
	v_pk_add_f32 v[64:65], v[64:65], v[232:233]
	v_mul_f32_e32 v73, v67, v67
	v_mul_f32_e32 v72, v65, v65
	v_pk_add_f32 v[62:63], v[62:63], v[230:231]
	v_fmac_f32_e32 v72, v64, v64
	v_fmac_f32_e32 v73, v66, v66
	v_add_f32_e32 v72, v72, v73
	v_mul_f32_e32 v73, v61, v61
	v_mul_f32_e32 v74, v63, v63
	global_store_dwordx4 v[70:71], v[64:67], off
	global_store_dwordx4 v[70:71], v[60:63], off offset:16
	v_fmac_f32_e32 v73, v60, v60
	v_fmac_f32_e32 v74, v62, v62
	v_cvt_pk_bf16_f32 v64, v64, v65
	v_cvt_pk_bf16_f32 v65, v66, v67
	v_cvt_pk_bf16_f32 v66, v60, v61
	v_lshlrev_b64 v[60:61], 12, v[68:69]
	v_add_f32_e32 v73, v73, v74
	v_lshl_add_u64 v[60:61], s[2:3], 0, v[60:61]
	v_add_f32_e32 v74, v72, v73
	v_cvt_pk_bf16_f32 v67, v62, v63
	v_lshl_add_u64 v[72:73], v[144:145], 1, v[60:61]
	global_store_dwordx4 v[72:73], v[64:67], off
	s_waitcnt vmcnt(26)
	v_pk_add_f32 v[52:53], v[52:53], v[236:237]
	v_pk_add_f32 v[58:59], v[58:59], v[242:243]
	v_pk_add_f32 v[56:57], v[56:57], v[240:241]
	v_mul_f32_e32 v61, v59, v59
	v_mul_f32_e32 v60, v57, v57
	v_pk_add_f32 v[54:55], v[54:55], v[238:239]
	s_mov_b32 s88, 0x160000
	s_mov_b32 s89, 0
	v_lshl_add_u64 v[212:213], v[204:205], 0, s[88:89]
	global_load_dwordx4 v[228:231], v[212:213], off offset:16
	global_load_dwordx4 v[232:235], v[212:213], off
	global_load_dwordx4 v[236:239], v[212:213], off offset:528
	global_load_dwordx4 v[240:243], v[212:213], off offset:512
	v_fmac_f32_e32 v60, v56, v56
	v_fmac_f32_e32 v61, v58, v58
	v_add_f32_e32 v60, v60, v61
	v_mul_f32_e32 v61, v53, v53
	v_mul_f32_e32 v62, v55, v55
	v_fmac_f32_e32 v61, v52, v52
	v_fmac_f32_e32 v62, v54, v54
	v_add_f32_e32 v61, v61, v62
	v_add_f32_e32 v60, v60, v61
	v_add_f32_e32 v60, v74, v60
	global_store_dwordx4 v[70:71], v[56:59], off offset:512
	global_store_dwordx4 v[70:71], v[52:55], off offset:528
	s_nop 0
	v_cvt_pk_bf16_f32 v56, v56, v57
	v_cvt_pk_bf16_f32 v57, v58, v59
	v_cvt_pk_bf16_f32 v58, v52, v53
	ds_bpermute_b32 v52, v167, v60
	v_cvt_pk_bf16_f32 v59, v54, v55
	global_store_dwordx4 v[72:73], v[56:59], off offset:256
	s_waitcnt lgkmcnt(0)
	v_add_f32_e32 v52, v60, v52
	ds_bpermute_b32 v53, v166, v52
	s_and_saveexec_b64 s[4:5], s[36:37]
	s_cbranch_execz .LBB0_2870
	v_readlane_b32 s2, v250, 11
	v_lshlrev_b64 v[54:55], 7, v[68:69]
	v_readlane_b32 s3, v250, 12
	s_lshl_b32 s6, s56, 2
	s_waitcnt lgkmcnt(0)
	v_add_f32_e32 v52, v52, v53
	v_lshl_add_u64 v[54:55], s[2:3], 0, v[54:55]
	v_readlane_b32 s2, v253, 17
	v_readlane_b32 s3, v253, 18
	v_lshl_add_u64 v[54:55], s[0:1], 2, v[54:55]
	s_mov_b32 s7, s3
	v_writelane_b32 v253, s2, 17
	v_lshl_add_u64 v[54:55], v[54:55], 0, s[6:7]
	global_store_dword v[54:55], v52, off
	v_writelane_b32 v253, s3, 18
.LBB0_2870:
	s_or_b64 exec, exec, s[4:5]
	v_add_u32_e32 v52, 0x90, v146
	s_waitcnt lgkmcnt(0)
	v_ashrrev_i32_e32 v53, 31, v52
	v_readlane_b32 s2, v250, 9
	v_lshlrev_b64 v[54:55], 13, v[52:53]
	v_readlane_b32 s3, v250, 10
	s_nop 1
	v_lshl_add_u64 v[54:55], s[2:3], 0, v[54:55]
	v_lshl_add_u64 v[54:55], v[144:145], 2, v[54:55]
	v_readlane_b32 s2, v252, 15
	v_readlane_b32 s3, v252, 16
	s_waitcnt vmcnt(25)
	v_pk_add_f32 v[44:45], v[44:45], v[192:193]
	v_pk_add_f32 v[50:51], v[50:51], v[198:199]
	v_pk_add_f32 v[48:49], v[48:49], v[196:197]
	v_mul_f32_e32 v57, v51, v51
	v_mul_f32_e32 v56, v49, v49
	v_pk_add_f32 v[46:47], v[46:47], v[194:195]
	v_fmac_f32_e32 v56, v48, v48
	v_fmac_f32_e32 v57, v50, v50
	v_add_f32_e32 v56, v56, v57
	v_mul_f32_e32 v57, v45, v45
	v_mul_f32_e32 v58, v47, v47
	global_store_dwordx4 v[54:55], v[48:51], off
	global_store_dwordx4 v[54:55], v[44:47], off offset:16
	v_fmac_f32_e32 v57, v44, v44
	v_fmac_f32_e32 v58, v46, v46
	v_cvt_pk_bf16_f32 v48, v48, v49
	v_cvt_pk_bf16_f32 v49, v50, v51
	v_cvt_pk_bf16_f32 v50, v44, v45
	v_lshlrev_b64 v[44:45], 12, v[52:53]
	v_add_f32_e32 v57, v57, v58
	v_lshl_add_u64 v[44:45], s[2:3], 0, v[44:45]
	v_add_f32_e32 v58, v56, v57
	v_cvt_pk_bf16_f32 v51, v46, v47
	v_lshl_add_u64 v[56:57], v[144:145], 1, v[44:45]
	global_store_dwordx4 v[56:57], v[48:51], off
	s_waitcnt vmcnt(26)
	v_pk_add_f32 v[36:37], v[36:37], v[200:201]
	v_pk_add_f32 v[42:43], v[42:43], v[246:247]
	v_pk_add_f32 v[40:41], v[40:41], v[244:245]
	v_mul_f32_e32 v45, v43, v43
	v_mul_f32_e32 v44, v41, v41
	v_pk_add_f32 v[38:39], v[38:39], v[202:203]
	v_fmac_f32_e32 v44, v40, v40
	v_fmac_f32_e32 v45, v42, v42
	v_add_f32_e32 v44, v44, v45
	v_mul_f32_e32 v45, v37, v37
	v_mul_f32_e32 v46, v39, v39
	v_fmac_f32_e32 v45, v36, v36
	v_fmac_f32_e32 v46, v38, v38
	v_add_f32_e32 v45, v45, v46
	v_add_f32_e32 v44, v44, v45
	v_add_f32_e32 v44, v58, v44
	global_store_dwordx4 v[54:55], v[40:43], off offset:512
	global_store_dwordx4 v[54:55], v[36:39], off offset:528
	s_nop 0
	v_cvt_pk_bf16_f32 v40, v40, v41
	v_cvt_pk_bf16_f32 v41, v42, v43
	v_cvt_pk_bf16_f32 v42, v36, v37
	ds_bpermute_b32 v36, v167, v44
	v_cvt_pk_bf16_f32 v43, v38, v39
	global_store_dwordx4 v[56:57], v[40:43], off offset:256
	s_waitcnt lgkmcnt(0)
	v_add_f32_e32 v36, v44, v36
	ds_bpermute_b32 v37, v166, v36
	s_and_saveexec_b64 s[4:5], s[36:37]
	s_cbranch_execz .LBB0_2872
	v_readlane_b32 s2, v250, 11
	v_lshlrev_b64 v[38:39], 7, v[52:53]
	v_readlane_b32 s3, v250, 12
	s_lshl_b32 s6, s56, 2
	s_waitcnt lgkmcnt(0)
	v_add_f32_e32 v36, v36, v37
	v_lshl_add_u64 v[38:39], s[2:3], 0, v[38:39]
	v_readlane_b32 s2, v253, 17
	v_readlane_b32 s3, v253, 18
	v_lshl_add_u64 v[38:39], s[0:1], 2, v[38:39]
	s_mov_b32 s7, s3
	v_writelane_b32 v253, s2, 17
	v_lshl_add_u64 v[38:39], v[38:39], 0, s[6:7]
	global_store_dword v[38:39], v36, off
	v_writelane_b32 v253, s3, 18
.LBB0_2872:
	s_or_b64 exec, exec, s[4:5]
	v_add_u32_e32 v36, 0xa0, v146
	s_waitcnt lgkmcnt(0)
	v_ashrrev_i32_e32 v37, 31, v36
	v_readlane_b32 s2, v250, 9
	v_lshlrev_b64 v[38:39], 13, v[36:37]
	v_readlane_b32 s3, v250, 10
	s_nop 1
	v_lshl_add_u64 v[38:39], s[2:3], 0, v[38:39]
	v_lshl_add_u64 v[38:39], v[144:145], 2, v[38:39]
	v_readlane_b32 s2, v252, 15
	v_readlane_b32 s3, v252, 16
	s_waitcnt vmcnt(21)
	v_pk_add_f32 v[28:29], v[28:29], v[176:177]
	v_pk_add_f32 v[34:35], v[34:35], v[182:183]
	v_pk_add_f32 v[32:33], v[32:33], v[180:181]
	v_mul_f32_e32 v41, v35, v35
	v_mul_f32_e32 v40, v33, v33
	v_pk_add_f32 v[30:31], v[30:31], v[178:179]
	v_fmac_f32_e32 v40, v32, v32
	v_fmac_f32_e32 v41, v34, v34
	v_add_f32_e32 v40, v40, v41
	v_mul_f32_e32 v41, v29, v29
	v_mul_f32_e32 v42, v31, v31
	global_store_dwordx4 v[38:39], v[32:35], off
	global_store_dwordx4 v[38:39], v[28:31], off offset:16
	v_fmac_f32_e32 v41, v28, v28
	v_fmac_f32_e32 v42, v30, v30
	v_cvt_pk_bf16_f32 v32, v32, v33
	v_cvt_pk_bf16_f32 v33, v34, v35
	v_cvt_pk_bf16_f32 v34, v28, v29
	v_lshlrev_b64 v[28:29], 12, v[36:37]
	v_add_f32_e32 v41, v41, v42
	v_lshl_add_u64 v[28:29], s[2:3], 0, v[28:29]
	v_add_f32_e32 v42, v40, v41
	v_cvt_pk_bf16_f32 v35, v30, v31
	v_lshl_add_u64 v[40:41], v[144:145], 1, v[28:29]
	global_store_dwordx4 v[40:41], v[32:35], off
	s_waitcnt vmcnt(22)
	v_pk_add_f32 v[20:21], v[20:21], v[184:185]
	v_pk_add_f32 v[26:27], v[26:27], v[190:191]
	v_pk_add_f32 v[24:25], v[24:25], v[188:189]
	v_mul_f32_e32 v29, v27, v27
	v_mul_f32_e32 v28, v25, v25
	v_pk_add_f32 v[22:23], v[22:23], v[186:187]
	v_fmac_f32_e32 v28, v24, v24
	v_fmac_f32_e32 v29, v26, v26
	v_add_f32_e32 v28, v28, v29
	v_mul_f32_e32 v29, v21, v21
	v_mul_f32_e32 v30, v23, v23
	v_fmac_f32_e32 v29, v20, v20
	v_fmac_f32_e32 v30, v22, v22
	v_add_f32_e32 v29, v29, v30
	v_add_f32_e32 v28, v28, v29
	v_add_f32_e32 v28, v42, v28
	global_store_dwordx4 v[38:39], v[24:27], off offset:512
	global_store_dwordx4 v[38:39], v[20:23], off offset:528
	s_nop 0
	v_cvt_pk_bf16_f32 v24, v24, v25
	v_cvt_pk_bf16_f32 v25, v26, v27
	v_cvt_pk_bf16_f32 v26, v20, v21
	ds_bpermute_b32 v20, v167, v28
	v_cvt_pk_bf16_f32 v27, v22, v23
	global_store_dwordx4 v[40:41], v[24:27], off offset:256
	s_waitcnt lgkmcnt(0)
	v_add_f32_e32 v20, v28, v20
	ds_bpermute_b32 v21, v166, v20
	s_and_saveexec_b64 s[4:5], s[36:37]
	s_cbranch_execz .LBB0_2874
	v_readlane_b32 s2, v250, 11
	v_lshlrev_b64 v[22:23], 7, v[36:37]
	v_readlane_b32 s3, v250, 12
	s_lshl_b32 s6, s56, 2
	s_waitcnt lgkmcnt(0)
	v_add_f32_e32 v20, v20, v21
	v_lshl_add_u64 v[22:23], s[2:3], 0, v[22:23]
	v_readlane_b32 s2, v253, 17
	v_readlane_b32 s3, v253, 18
	v_lshl_add_u64 v[22:23], s[0:1], 2, v[22:23]
	s_mov_b32 s7, s3
	v_writelane_b32 v253, s2, 17
	v_lshl_add_u64 v[22:23], v[22:23], 0, s[6:7]
	global_store_dword v[22:23], v20, off
	v_writelane_b32 v253, s3, 18
.LBB0_2874:
	s_or_b64 exec, exec, s[4:5]
	v_add_u32_e32 v20, 0xb0, v146
	s_waitcnt lgkmcnt(0)
	v_ashrrev_i32_e32 v21, 31, v20
	v_readlane_b32 s2, v250, 9
	v_lshlrev_b64 v[22:23], 13, v[20:21]
	v_readlane_b32 s3, v250, 10
	s_nop 1
	v_lshl_add_u64 v[22:23], s[2:3], 0, v[22:23]
	v_lshl_add_u64 v[22:23], v[144:145], 2, v[22:23]
	v_readlane_b32 s2, v252, 15
	v_readlane_b32 s3, v252, 16
	s_waitcnt vmcnt(17)
	v_pk_add_f32 v[12:13], v[12:13], v[228:229]
	v_pk_add_f32 v[18:19], v[18:19], v[234:235]
	v_pk_add_f32 v[16:17], v[16:17], v[232:233]
	v_mul_f32_e32 v25, v19, v19
	v_mul_f32_e32 v24, v17, v17
	v_pk_add_f32 v[14:15], v[14:15], v[230:231]
	v_fmac_f32_e32 v24, v16, v16
	v_fmac_f32_e32 v25, v18, v18
	v_add_f32_e32 v24, v24, v25
	v_mul_f32_e32 v25, v13, v13
	v_mul_f32_e32 v26, v15, v15
	global_store_dwordx4 v[22:23], v[16:19], off
	global_store_dwordx4 v[22:23], v[12:15], off offset:16
	v_fmac_f32_e32 v25, v12, v12
	v_fmac_f32_e32 v26, v14, v14
	v_cvt_pk_bf16_f32 v16, v16, v17
	v_cvt_pk_bf16_f32 v17, v18, v19
	v_cvt_pk_bf16_f32 v18, v12, v13
	v_lshlrev_b64 v[12:13], 12, v[20:21]
	v_add_f32_e32 v25, v25, v26
	v_lshl_add_u64 v[12:13], s[2:3], 0, v[12:13]
	v_add_f32_e32 v26, v24, v25
	v_cvt_pk_bf16_f32 v19, v14, v15
	v_lshl_add_u64 v[24:25], v[144:145], 1, v[12:13]
	global_store_dwordx4 v[24:25], v[16:19], off
	s_waitcnt vmcnt(18)
	v_pk_add_f32 v[2:3], v[2:3], v[236:237]
	v_pk_add_f32 v[8:9], v[8:9], v[242:243]
	v_pk_add_f32 v[6:7], v[6:7], v[240:241]
	v_mul_f32_e32 v13, v9, v9
	v_mul_f32_e32 v12, v7, v7
	v_pk_add_f32 v[4:5], v[4:5], v[238:239]
	v_fmac_f32_e32 v12, v6, v6
	v_fmac_f32_e32 v13, v8, v8
	v_add_f32_e32 v12, v12, v13
	v_mul_f32_e32 v13, v3, v3
	v_mul_f32_e32 v14, v5, v5
	v_fmac_f32_e32 v13, v2, v2
	v_fmac_f32_e32 v14, v4, v4
	v_add_f32_e32 v13, v13, v14
	v_add_f32_e32 v12, v12, v13
	v_add_f32_e32 v12, v26, v12
	global_store_dwordx4 v[22:23], v[6:9], off offset:512
	global_store_dwordx4 v[22:23], v[2:5], off offset:528
	s_nop 0
	v_cvt_pk_bf16_f32 v6, v6, v7
	v_cvt_pk_bf16_f32 v7, v8, v9
	v_cvt_pk_bf16_f32 v8, v2, v3
	ds_bpermute_b32 v2, v167, v12
	v_cvt_pk_bf16_f32 v9, v4, v5
	global_store_dwordx4 v[24:25], v[6:9], off offset:256
	s_waitcnt lgkmcnt(0)
	v_add_f32_e32 v2, v12, v2
	ds_bpermute_b32 v3, v166, v2
	s_and_saveexec_b64 s[4:5], s[36:37]
	s_cbranch_execz .LBB0_2876
	v_readlane_b32 s2, v250, 11
	v_lshlrev_b64 v[4:5], 7, v[20:21]
	v_readlane_b32 s3, v250, 12
	s_waitcnt lgkmcnt(0)
	v_add_f32_e32 v2, v2, v3
	v_lshl_add_u64 v[4:5], s[2:3], 0, v[4:5]
	v_lshl_add_u64 v[4:5], s[0:1], 2, v[4:5]
	v_readlane_b32 s0, v253, 17
	v_readlane_b32 s1, v253, 18
	s_mov_b32 s3, s1
	s_lshl_b32 s2, s56, 2
	v_writelane_b32 v253, s0, 17
	v_lshl_add_u64 v[4:5], v[4:5], 0, s[2:3]
	global_store_dword v[4:5], v2, off
	v_writelane_b32 v253, s1, 18

	.amdhsa_kernel _Z3fwd4Args
		.amdhsa_group_segment_fixed_size 0
		.amdhsa_private_segment_fixed_size 0
		.amdhsa_kernarg_size 520
		.amdhsa_user_sgpr_count 2
		.amdhsa_user_sgpr_dispatch_ptr 0
		.amdhsa_user_sgpr_queue_ptr 0
		.amdhsa_user_sgpr_kernarg_segment_ptr 1
		.amdhsa_user_sgpr_dispatch_id 0
		.amdhsa_user_sgpr_kernarg_preload_length 0
		.amdhsa_user_sgpr_kernarg_preload_offset 0
		.amdhsa_user_sgpr_private_segment_size 0
		.amdhsa_uses_dynamic_stack 0
		.amdhsa_enable_private_segment 0
		.amdhsa_system_sgpr_workgroup_id_x 1
		.amdhsa_system_sgpr_workgroup_id_y 0
		.amdhsa_system_sgpr_workgroup_id_z 0
		.amdhsa_system_sgpr_workgroup_info 0
		.amdhsa_system_vgpr_workitem_id 0
		.amdhsa_next_free_vgpr 256
		.amdhsa_next_free_sgpr 102
		.amdhsa_accum_offset 256
		.amdhsa_reserve_vcc 1
		.amdhsa_float_round_mode_32 0
		.amdhsa_float_round_mode_16_64 0
		.amdhsa_float_denorm_mode_32 3
		.amdhsa_float_denorm_mode_16_64 3
		.amdhsa_dx10_clamp 1
		.amdhsa_ieee_mode 1
		.amdhsa_fp16_overflow 0
		.amdhsa_tg_split 0
		.amdhsa_exception_fp_ieee_invalid_op 0
		.amdhsa_exception_fp_denorm_src 0
		.amdhsa_exception_fp_ieee_div_zero 0
		.amdhsa_exception_fp_ieee_overflow 0
		.amdhsa_exception_fp_ieee_underflow 0
		.amdhsa_exception_fp_ieee_inexact 0
		.amdhsa_exception_int_div_zero 0
	.end_amdhsa_kernel

amdhsa.kernels:
  - .agpr_count:     0
    .args:
      - .offset:         0
        .size:           264
        .value_kind:     by_value
      - .offset:         264
        .size:           4
        .value_kind:     hidden_block_count_x
      - .offset:         268
        .size:           4
        .value_kind:     hidden_block_count_y
      - .offset:         272
        .size:           4
        .value_kind:     hidden_block_count_z
      - .offset:         276
        .size:           2
        .value_kind:     hidden_group_size_x
      - .offset:         278
        .size:           2
        .value_kind:     hidden_group_size_y
      - .offset:         280
        .size:           2
        .value_kind:     hidden_group_size_z
      - .offset:         282
        .size:           2
        .value_kind:     hidden_remainder_x
      - .offset:         284
        .size:           2
        .value_kind:     hidden_remainder_y
      - .offset:         286
        .size:           2
        .value_kind:     hidden_remainder_z
      - .offset:         304
        .size:           8
        .value_kind:     hidden_global_offset_x
      - .offset:         312
        .size:           8
        .value_kind:     hidden_global_offset_y
      - .offset:         320
        .size:           8
        .value_kind:     hidden_global_offset_z
      - .offset:         328
        .size:           2
        .value_kind:     hidden_grid_dims
      - .offset:         384
        .size:           4
        .value_kind:     hidden_dynamic_lds_size
    .group_segment_fixed_size: 0
    .kernarg_segment_align: 8
    .kernarg_segment_size: 520
    .language:       OpenCL C
    .language_version:
      - 2
      - 0
    .max_flat_workgroup_size: 512
    .name:           _Z3fwd4Args
    .private_segment_fixed_size: 0
    .sgpr_count:     108
    .sgpr_spill_count: 509
    .symbol:         _Z3fwd4Args.kd
    .uniform_work_group_size: 1
    .uses_dynamic_stack: false
    .vgpr_count:     256
    .vgpr_spill_count: 0
    .wavefront_size: 64
